# ctx rows of Wo/down GEMMs (layers 0-2) via register-tiled MFMA routine; main GEMM in latent-only (skip) mode
# speedup vs baseline: 1.0403x; 1.0045x over previous
; __global__ void __launch_bounds__(512) fwd_kernel(Params p) {
;     ...
;                 GemmJob gj; gj.crot = 0; gj.skip = 0; gj.o1 = nullptr; gj.rope = nullptr; gj.mode = 0; gj.ldc = D; gj.K = D; gj.M = MTOT; gj.N = D; gj.epi = 0; gj.o0 = nullptr; gj.A = HB; gj.Bt = WLp;
;                 if (ph == 0) {
;                     if (kind == 1) { gj.Bt = WLp + W_WIN; gj.N = 768; gj.o0 = Zb; gj.ldc = 768; }
;                     else if (j == 0) { gj.Bt = WLp + W_MX; gj.N = 2048; gj.epi = 1; gj.o0 = Qb; gj.o1 = Kb; gj.mode = (kind == 0) ? 0 : 3; gj.rope = ROPEA; }
;                     else { gj.A = WLp + W_MX + (size_t)2048 * D; gj.Bt = HB; gj.M = D; gj.N = MTOT; gj.o0 = Vtb; gj.ldc = MTOT; gj.crot = G / 2; }
;                 } else if (ph == 2) {
;                     gj.K = 256;
;                     if (j == 0) { gj.A = CQ; gj.Bt = WLp + W_WUQ; gj.N = 1536; gj.epi = 1; gj.o0 = Qb; gj.o1 = Kb; gj.mode = 1; gj.rope = ROPEB; }
;                     else if (j == 1) { gj.A = CKV; gj.Bt = WLp + W_WUKV; gj.N = 1024; gj.epi = 1; gj.o0 = Qb; gj.o1 = Kb; gj.mode = 2; gj.crot = G / 4; }
;                     else { gj.A = WLp + W_WUKV + (size_t)1024 * 256; gj.Bt = CKV; gj.M = 1024; gj.N = MTOT; gj.o0 = Vtb; gj.ldc = MTOT; gj.crot = G / 2; }
;                 } else if (ph == 5) { gj.A = (kind == 0) ? HB : Ob; gj.Bt = WLp + W_WO; gj.o0 = Yb; }
;                 else if (ph == 7) { gj.Bt = WLp + W_GU; gj.N = 2 * FF; gj.epi = 2; gj.o0 = ACT; }
;                 else { gj.A = ACT; gj.Bt = WLp + W_DN; gj.K = FF; gj.o0 = HB; }
;                 if (l == 3 && ph >= 5) { gj.M = NB * SEQ; gj.skip = 1; }
;                 pg8::StaticOrder S; S.init(gj.M, gj.N, G, (bx + gj.crot) % G, gj.skip);
.LBB0_331:
	s_cmp_eq_u32 s19, 0
	s_cbranch_scc1 .LBB0_486
	v_readlane_b32 s6, v252, 7
	v_mov_b32_e32 v8, 1
	v_and_b32_e32 v155, 15, v0
	v_add_u32_e32 v154, s6, v0
	s_add_u32 s6, s0, 0xa00000
	v_writelane_b32 v253, s6, 0
	s_addc_u32 s6, s1, 0
	v_writelane_b32 v253, s6, 2
	s_add_u32 s6, s0, 0xc00000
	s_addc_u32 s7, s1, 0
	s_add_u32 s14, s0, 0x7300000
	s_addc_u32 s15, s1, 0
	v_writelane_b32 v253, s6, 4
	s_add_u32 s16, s0, 0xb500000
	s_addc_u32 s17, s1, 0
	v_writelane_b32 v253, s7, 5
	s_mul_hi_i32 s6, s9, 0x1880000
	s_mul_i32 s9, s9, 0x1880000
	s_add_u32 s9, s0, s9
	s_addc_u32 s10, s1, s6
	s_add_u32 s6, s9, 0x1100000
	s_addc_u32 s7, s10, 0
	v_writelane_b32 v253, s6, 6
	v_bfe_i32 v4, v154, 27, 1
	v_lshlrev_b32_e32 v2, 4, v154
	v_writelane_b32 v253, s7, 7
	s_and_b64 s[6:7], s[4:5], exec
	s_mov_b32 s6, 0x6300000
	s_cselect_b32 s6, s6, 0x4200000
	s_add_u32 s6, s16, s6
	s_addc_u32 s7, s17, 0
	v_writelane_b32 v253, s6, 8
	v_lshrrev_b32_e32 v4, 22, v4
	v_add_u32_e32 v4, v2, v4
	v_writelane_b32 v253, s7, 9
	s_and_b64 s[6:7], s[4:5], exec
	s_mov_b32 s6, 0xc600000
	s_cselect_b32 s6, s6, 0x8400000
	s_add_u32 s6, s16, s6
	s_addc_u32 s7, s17, 0
	s_and_b64 s[4:5], s[4:5], exec
	s_mov_b32 s4, 0x10800000
	s_cselect_b32 s4, s4, 0xc600000
	s_add_u32 s4, s16, s4
	v_writelane_b32 v253, s6, 10
	s_addc_u32 s5, s17, 0
	v_and_b32_e32 v4, 0xfffffc00, v4
	v_writelane_b32 v253, s7, 11
	s_add_u32 s6, s0, 0x1bd00000
	s_addc_u32 s7, s1, 0
	v_writelane_b32 v253, s6, 12
	s_add_u32 s0, s0, 0x8380000
	s_addc_u32 s1, s1, 0
	v_writelane_b32 v253, s7, 13
	v_writelane_b32 v253, s0, 14
	v_sub_u32_e32 v4, v2, v4
	v_ashrrev_i32_e32 v3, 31, v154
	v_writelane_b32 v253, s1, 15
	s_add_u32 s0, s9, 0x2780000
	s_addc_u32 s1, s10, 0
	v_writelane_b32 v253, s0, 16
	v_lshrrev_b32_e32 v5, 4, v4
	v_lshrrev_b32_e32 v3, 26, v3
	v_writelane_b32 v253, s1, 17
	s_add_u32 s0, s9, 0x23c0000
	s_addc_u32 s1, s10, 0
	v_writelane_b32 v253, s0, 18
	v_bitop3_b32 v4, v5, v4, 32 bitop3:0x6c
	v_add_u32_e32 v3, v154, v3
	v_writelane_b32 v253, s1, 19
	s_add_u32 s0, s9, 0x2300000
	s_addc_u32 s1, s10, 0
	v_writelane_b32 v253, s0, 20
	v_ashrrev_i32_e32 v6, 31, v4
	v_ashrrev_i32_e32 v3, 6, v3
	v_writelane_b32 v253, s1, 21
	s_add_u32 s0, s9, 0x2440000
	s_addc_u32 s1, s10, 0
	v_writelane_b32 v253, s0, 22
	v_lshrrev_b32_e32 v6, 26, v6
	v_lshlrev_b32_e32 v5, 3, v3
	v_writelane_b32 v253, s1, 23
	s_add_u32 s0, s9, 0x1c00000
	s_addc_u32 s1, s10, 0
	v_writelane_b32 v253, s0, 24
	v_add_u32_e32 v6, v4, v6
	v_and_b32_e32 v5, -16, v5
	v_writelane_b32 v253, s1, 25
	s_add_u32 s0, s9, 0x2580000
	v_writelane_b32 v253, s0, 26
	s_addc_u32 s0, s10, 0
	v_writelane_b32 v253, s0, 28
	s_add_u32 s0, s9, 0x2180000
	s_addc_u32 s1, s10, 0
	v_writelane_b32 v253, s0, 30
	s_cmp_eq_u32 s8, 0
	v_ashrrev_i32_e32 v7, 6, v6
	v_writelane_b32 v253, s1, 31
	s_cselect_b32 s1, s15, s5
	s_cselect_b32 s0, s14, s4
	v_writelane_b32 v253, s0, 32
	v_add_u32_e32 v156, v7, v5
	v_and_b32_e32 v5, 0xc0, v6
	v_writelane_b32 v253, s1, 33
	s_cselect_b32 s0, 0, 3
	v_writelane_b32 v253, s0, 34
	s_sub_i32 s0, s2, 40
	s_cmp_lt_u32 s0, -10
	s_cselect_b64 s[0:1], -1, 0
	s_cmp_lt_i32 s69, 5
	v_lshlrev_b32_e32 v3, 5, v3
	v_sub_u32_e32 v4, v4, v5
	s_cselect_b64 s[4:5], -1, 0
	v_and_b32_e32 v3, 32, v3
	v_ashrrev_i16_sdwa v4, v8, sext(v4) dst_sel:DWORD dst_unused:UNUSED_PAD src0_sel:DWORD src1_sel:BYTE_0
	s_or_b64 s[44:45], s[0:1], s[4:5]
	s_cmp_eq_u32 s69, 7
	s_cselect_b64 s[44:45], -1, 0
	s_and_b64 s[44:45], s[44:45], s[0:1]
	s_or_b64 s[44:45], s[44:45], s[4:5]
	v_add_u32_sdwa v157, v3, sext(v4) dst_sel:DWORD dst_unused:UNUSED_PAD src0_sel:DWORD src1_sel:WORD_0
	v_lshlrev_b32_e32 v3, 1, v156
	v_lshrrev_b32_e32 v4, 2, v156
	v_and_b32_e32 v5, 3, v7
	s_mov_b32 s0, 0x7fffffe0
	v_and_b32_e32 v3, 24, v3
	v_and_b32_e32 v4, 4, v4
	v_and_or_b32 v5, v156, s0, v5
	v_add_u32_e32 v2, 0x2000, v2
	v_or3_b32 v158, v5, v4, v3
	v_ashrrev_i32_e32 v3, 31, v2
	v_lshrrev_b32_e32 v3, 22, v3
	v_add_u32_e32 v3, v2, v3
	v_ashrrev_i32_e32 v3, 10, v3
	v_mul_i32_i24_e32 v4, 0x400, v3
	v_sub_u32_e32 v2, v2, v4
	v_lshrrev_b32_e32 v4, 4, v2
	v_bitop3_b32 v2, v4, v2, 32 bitop3:0x6c
	v_ashrrev_i32_e32 v5, 31, v2
	v_lshrrev_b32_e32 v5, 26, v5
	v_lshlrev_b32_e32 v4, 3, v3
	v_add_u32_e32 v5, v2, v5
	v_and_b32_e32 v4, -16, v4
	v_ashrrev_i32_e32 v6, 6, v5
	v_add_u32_e32 v159, v6, v4
	v_and_b32_e32 v4, 0xc0, v5
	v_lshlrev_b32_e32 v3, 5, v3
	v_sub_u32_e32 v2, v2, v4
	v_and_b32_e32 v3, 32, v3
	v_ashrrev_i16_sdwa v2, v8, sext(v2) dst_sel:DWORD dst_unused:UNUSED_PAD src0_sel:DWORD src1_sel:BYTE_0
	v_add_u32_sdwa v160, v3, sext(v2) dst_sel:DWORD dst_unused:UNUSED_PAD src0_sel:DWORD src1_sel:WORD_0
	v_lshlrev_b32_e32 v2, 1, v159
	v_lshrrev_b32_e32 v3, 2, v159
	v_and_b32_e32 v4, 3, v6
	v_writelane_b32 v253, s69, 36
	v_and_b32_e32 v2, 24, v2
	v_and_b32_e32 v3, 4, v3
	v_and_or_b32 v4, v159, s0, v4
	v_writelane_b32 v253, s70, 38
	v_or3_b32 v161, v4, v3, v2
	v_lshrrev_b32_e32 v2, 1, v0
	v_lshlrev_b32_e32 v4, 2, v0
	v_lshrrev_b32_e32 v5, 4, v0
	v_bfe_u32 v0, v0, 4, 2
	v_writelane_b32 v253, s71, 39
	v_and_b32_e32 v162, 24, v2
	v_lshlrev_b32_e32 v164, 3, v0
	v_lshlrev_b32_e32 v165, 4, v0
	v_bfe_u32 v0, v5, 1, 1
	v_writelane_b32 v253, s20, 40
	v_lshlrev_b32_e32 v2, 1, v162
	v_lshlrev_b32_e32 v3, 6, v155
	v_and_b32_e32 v4, 32, v4
	v_or_b32_e32 v209, 0xffffffe0, v0
	v_lshlrev_b32_e32 v0, 2, v155
	v_writelane_b32 v253, s21, 41
	s_mov_b32 s12, 0
	v_bitop3_b32 v163, v2, v4, v3 bitop3:0x36
	v_bitop3_b32 v166, v165, v4, v3 bitop3:0x36
	v_and_b32_e32 v167, 8, v164
	v_lshl_or_b32 v206, v155, 6, v2
	v_and_b32_e32 v172, 32, v0
	v_writelane_b32 v253, s19, 42
	s_branch .LBB0_335

; #define GAS __attribute__((address_space(1)))
; DI u32x4 pack8(f32x4 a, f32x4 b) { u32x4 w; w.x = pk2(a[0], a[1]); w.y = pk2(a[2], a[3]); w.z = pk2(b[0], b[1]); w.w = pk2(b[2], b[3]); return w; }
;     DI void operator()(const AccT& acc, const pg8::Unit& u, int wr, int wc, int fr, int fq) const {
;         const int row0 = u.pm * 256 + wr * 64 + fr, col0 = u.pn * 256 + wc * 32 + 8 * fq;
; #pragma unroll
;         for (int ai = 0; ai < 2; ++ai)
; #pragma unroll
;             for (int m = 0; m < 4; ++m) { bf16_t* rowp = O + (size_t)(row0 + ai * 128 + m * 16) * ldc + col0;
; #pragma unroll
;                 for (int bj = 0; bj < 2; ++bj) *(GAS u32x4*)(rowp + bj * 128) = pack8(acc[ai][bj][m][0], acc[ai][bj][m][1]); }
;     }
; __global__ void __launch_bounds__(512) fwd_kernel(Params p) {
;     ...
;                 } else if (ph == 5) { gj.A = (kind == 0) ? HB : Ob; gj.Bt = WLp + W_WO; gj.o0 = Yb; }
;                 else if (ph == 7) { gj.Bt = WLp + W_GU; gj.N = 2 * FF; gj.epi = 2; gj.o0 = ACT; }
;                 else { gj.A = ACT; gj.Bt = WLp + W_DN; gj.K = FF; gj.o0 = HB; }
;                 if (l == 3 && ph >= 5) { gj.M = NB * SEQ; gj.skip = 1; }
.LBB0_486:
	v_readlane_b32 s2, v252, 63
	s_cmp_ge_u32 s2, 30
	s_cbranch_scc1 .Lcg0_done
	s_mul_hi_i32 s0, s2, 0x66666667
	s_lshr_b32 s1, s0, 31
	s_ashr_i32 s0, s0, 2
	s_add_i32 s4, s0, s1
	s_mul_i32 s0, s4, -10
	s_add_i32 s5, s0, s2
	s_cmp_eq_u32 s5, 5
	s_cbranch_scc1 .Lcg0_go
	s_cmp_eq_u32 s5, 8
	s_cbranch_scc0 .Lcg0_done
.Lcg0_go:
	v_readlane_b32 s1, v252, 7
	s_lshr_b32 s1, s1, 6
	s_cmp_ge_u32 s1, 2
	s_cbranch_scc1 .Lcg0_done
	s_mul_i32 s0, s4, 0x1880000
	s_add_u32 s8, s94, s0
	s_addc_u32 s9, s95, 0
	s_cmp_eq_u32 s5, 5
	s_mov_b32 s1, 0x1c00000
	s_cselect_b32 s0, 0x2780000, s1
	s_add_u32 s8, s8, s0
	s_addc_u32 s9, s9, 0
	s_cmp_eq_u32 s5, 5
	s_movk_i32 s1, 0xb00
	s_cselect_b32 s13, 0x400, s1
	s_mov_b32 s0, 0xb500000
	s_cmp_eq_u32 s5, 5
	s_cbranch_scc0 .Lcg0_a
	s_mov_b32 s0, 0x7300000
	s_cmp_eq_u32 s4, 0
	s_cbranch_scc1 .Lcg0_a
	s_mov_b32 s0, 0x1bd00000
	s_cmp_eq_u32 s4, 1
	s_cbranch_scc1 .Lcg0_a
	s_mov_b32 s0, 0x17b00000
.Lcg0_a:
	s_add_u32 s6, s94, s0
	s_addc_u32 s7, s95, 0
	s_cmp_eq_u32 s5, 5
	s_mov_b32 s1, 0x7300000
	s_cselect_b32 s0, 0xb500000, s1
	s_add_u32 s10, s94, s0
	s_addc_u32 s11, s95, 0
	v_writelane_b32 v2, s6, 0
	v_writelane_b32 v2, s7, 1
	v_writelane_b32 v2, s8, 2
	v_writelane_b32 v2, s9, 3
	v_writelane_b32 v2, s10, 4
	v_writelane_b32 v2, s11, 5
	v_writelane_b32 v2, s13, 6
	v_readlane_b32 s0, v252, 0
	v_readlane_b32 s1, v252, 7
	s_mul_i32 s0, s0, 2
	s_lshr_b32 s1, s1, 6
	s_add_i32 s2, s0, s1
	v_and_b32_e32 v5, 15, v171
	v_lshrrev_b32_e32 v6, 4, v171
	v_mul_lo_u32 v3, v5, s13
	v_lshlrev_b32_e32 v3, 1, v3
	v_lshl_add_u32 v3, v6, 4, v3
	v_lshlrev_b32_e32 v4, 11, v5
	v_lshl_add_u32 v4, v6, 3, v4
	v_mov_b32_e32 v7, 0
.Lcg0_tile:
	s_cmpk_ge_u32 s2, 512
	s_cbranch_scc1 .Lcg0_done
	v_readlane_b32 s6, v2, 0
	v_readlane_b32 s7, v2, 1
	v_readlane_b32 s8, v2, 2
	v_readlane_b32 s9, v2, 3
	v_readlane_b32 s10, v2, 4
	v_readlane_b32 s11, v2, 5
	v_readlane_b32 s13, v2, 6
	s_lshr_b32 s0, s2, 4
	s_mul_i32 s0, s0, 32
	s_lshr_b32 s1, s0, 8
	s_and_b32 s0, s0, 0xff
	s_mul_i32 s1, s1, 0x2100
	s_add_i32 s0, s0, s1
	s_lshl_b32 s1, s0, 11
	s_add_u32 s10, s10, s1
	s_addc_u32 s11, s11, 0
	s_and_b32 s1, s2, 15
	s_mul_i32 s1, s1, 128
	s_add_u32 s10, s10, s1
	s_addc_u32 s11, s11, 0
	s_mul_i32 s1, s0, s13
	s_lshl_b32 s1, s1, 1
	s_add_u32 s6, s6, s1
	s_addc_u32 s7, s7, 0
	s_and_b32 s1, s2, 15
	s_mul_i32 s1, s1, 128
	s_mul_i32 s1, s1, s13
	s_add_u32 s8, s8, s1
	s_addc_u32 s9, s9, 0
	s_lshl_b32 s4, s13, 5
	s_mov_b32 s5, 0
	v_mov_b32_e32 v8, s6
	v_mov_b32_e32 v9, s7
	v_mov_b32_e32 v152, v3
	v_mov_b32_e32 v153, 0
	v_lshl_add_u64 v[8:9], s[6:7], 0, v[152:153]
	v_lshl_add_u64 v[10:11], v[8:9], 0, s[4:5]
	v_lshl_add_u64 v[12:13], s[8:9], 0, v[152:153]
	v_lshl_add_u64 v[14:15], v[12:13], 0, s[4:5]
	v_lshl_add_u64 v[16:17], v[14:15], 0, s[4:5]
	v_lshl_add_u64 v[18:19], v[16:17], 0, s[4:5]
	s_lshr_b32 s12, s13, 5
	v_mov_b32_e32 v24, 0
	v_mov_b32_e32 v25, 0
	v_mov_b32_e32 v26, 0
	v_mov_b32_e32 v27, 0
	v_mov_b32_e32 v28, 0
	v_mov_b32_e32 v29, 0
	v_mov_b32_e32 v30, 0
	v_mov_b32_e32 v31, 0
	v_mov_b32_e32 v32, 0
	v_mov_b32_e32 v33, 0
	v_mov_b32_e32 v34, 0
	v_mov_b32_e32 v35, 0
	v_mov_b32_e32 v36, 0
	v_mov_b32_e32 v37, 0
	v_mov_b32_e32 v38, 0
	v_mov_b32_e32 v39, 0
	v_mov_b32_e32 v40, 0
	v_mov_b32_e32 v41, 0
	v_mov_b32_e32 v42, 0
	v_mov_b32_e32 v43, 0
	v_mov_b32_e32 v44, 0
	v_mov_b32_e32 v45, 0
	v_mov_b32_e32 v46, 0
	v_mov_b32_e32 v47, 0
	v_mov_b32_e32 v48, 0
	v_mov_b32_e32 v49, 0
	v_mov_b32_e32 v50, 0
	v_mov_b32_e32 v51, 0
	v_mov_b32_e32 v52, 0
	v_mov_b32_e32 v53, 0
	v_mov_b32_e32 v54, 0
	v_mov_b32_e32 v55, 0
	global_load_dwordx4 v[56:59], v[8:9], off offset:0
	global_load_dwordx4 v[60:63], v[10:11], off offset:0
	global_load_dwordx4 v[64:67], v[12:13], off offset:0
	global_load_dwordx4 v[68:71], v[14:15], off offset:0
	global_load_dwordx4 v[72:75], v[16:17], off offset:0
	global_load_dwordx4 v[76:79], v[18:19], off offset:0
	global_load_dwordx4 v[80:83], v[8:9], off offset:64
	global_load_dwordx4 v[84:87], v[10:11], off offset:64
	global_load_dwordx4 v[88:91], v[12:13], off offset:64
	global_load_dwordx4 v[92:95], v[14:15], off offset:64
	global_load_dwordx4 v[96:99], v[16:17], off offset:64
	global_load_dwordx4 v[100:103], v[18:19], off offset:64
	global_load_dwordx4 v[104:107], v[8:9], off offset:128
	global_load_dwordx4 v[108:111], v[10:11], off offset:128
	global_load_dwordx4 v[112:115], v[12:13], off offset:128
	global_load_dwordx4 v[116:119], v[14:15], off offset:128
	global_load_dwordx4 v[120:123], v[16:17], off offset:128
	global_load_dwordx4 v[124:127], v[18:19], off offset:128
	global_load_dwordx4 v[128:131], v[8:9], off offset:192
	global_load_dwordx4 v[132:135], v[10:11], off offset:192
	global_load_dwordx4 v[136:139], v[12:13], off offset:192
	global_load_dwordx4 v[140:143], v[14:15], off offset:192
	global_load_dwordx4 v[144:147], v[16:17], off offset:192
	global_load_dwordx4 v[148:151], v[18:19], off offset:192
	s_mov_b64 s[0:1], 256
	s_sub_i32 s12, s12, 4
; #define PG8_STAGE(bufoff, gbase, voff) do { _Pragma("unroll") for (int _i = 0; _i < 2; ++_i) \
;         __builtin_amdgcn_global_load_lds((const unsigned*)((const char*)(gbase) + (voff)[_i]), (LAS unsigned*)(lds + (bufoff) + ldsw + _i * 8192), 16, 0, 0); } while (0)
; #define PG8_LDA(dst, b, h) do { _Pragma("unroll") for (int m = 0; m < 4; ++m) _Pragma("unroll") for (int k = 0; k < 2; ++k) dst[m][k] = *(const LAS bf16x8*)(lds + PG8_SA(b, h) + aoff + m * 2048 + k * 1024); } while (0)
; #define PG8_LDB(dst, b, h) do { _Pragma("unroll") for (int n = 0; n < 2; ++n) _Pragma("unroll") for (int k = 0; k < 2; ++k) dst[n][k] = *(const LAS bf16x8*)(lds + PG8_SB(b, h) + boff + n * 2048 + k * 1024); } while (0)
; #define PG8_WAIT_V(n) asm volatile("s_waitcnt vmcnt(" #n ")" ::: "memory")
; #define PG8_BAR __builtin_amdgcn_s_barrier()
; template <class Epi, class Sched>
; __device__ __forceinline__ void gemm_phase(LAS unsigned char* lds, const Gemm g, const Sched& S, const Epi& E, const int tid) {
;     ...
;         for (int t = 0; t < nt; t += 2) {
;             const bool last = (t == nt - 2);
;             const char* a1 = cA + (size_t)(t + 1) * kstep;
;             const char* a2 = last ? nA : cA + (size_t)(t + 2) * kstep; const char* b2 = last ? nB : cB + (size_t)(t + 2) * kstep;
;             const char* a3 = a2 + kstep; const char* b3 = b2 + kstep;
;             PG8_LDB(B0, 0, 0); PG8_LDB(B1, 0, 1); PG8_SCHED; PG8_LDA(At, 0, 0); PG8_STAGE(PG8_SA(1, 1), a1 + hstep, voffA);
;             PG8_WAIT_V(8); PG8_WAIT_L(0); PG8_BAR; PG8_MMA(0, 0, At, B0); PG8_MMA(0, 1, At, B1); PG8_BAR; PG8_SCHED;
;             PG8_LDA(At, 0, 1); PG8_STAGE(PG8_SB(0, 0), b2, voffB); PG8_STAGE(PG8_SB(0, 1), b2 + hstep, voffB); PG8_STAGE(PG8_SA(0, 0), a2, voffA);
;             PG8_WAIT_V(8); PG8_WAIT_L(0); PG8_BAR; PG8_MMA(1, 0, At, B0); PG8_MMA(1, 1, At, B1); PG8_BAR; PG8_SCHED;
;             PG8_LDB(B0, 1, 0); PG8_LDB(B1, 1, 1); PG8_SCHED; PG8_LDA(At, 1, 0); PG8_STAGE(PG8_SA(0, 1), a2 + hstep, voffA);
;             PG8_WAIT_V(8); PG8_WAIT_L(0); PG8_BAR; PG8_MMA(0, 0, At, B0); PG8_MMA(0, 1, At, B1); PG8_BAR; PG8_SCHED;
;             PG8_LDA(At, 1, 1); PG8_STAGE(PG8_SB(1, 0), b3, voffB); PG8_STAGE(PG8_SB(1, 1), b3 + hstep, voffB); PG8_STAGE(PG8_SA(1, 0), a3, voffA);
;             PG8_WAIT_V(8); PG8_WAIT_L(0); PG8_BAR; PG8_MMA(1, 0, At, B0); PG8_MMA(1, 1, At, B1); PG8_BAR; PG8_SCHED;
.Lcg0_grp:
	v_lshl_add_u64 v[8:9], v[8:9], 0, s[0:1]
	v_lshl_add_u64 v[10:11], v[10:11], 0, s[0:1]
	v_lshl_add_u64 v[12:13], v[12:13], 0, s[0:1]
	v_lshl_add_u64 v[14:15], v[14:15], 0, s[0:1]
	v_lshl_add_u64 v[16:17], v[16:17], 0, s[0:1]
	v_lshl_add_u64 v[18:19], v[18:19], 0, s[0:1]
	s_waitcnt vmcnt(18)
	v_mfma_f32_16x16x32_bf16 v[24:27], v[64:67], v[56:59], v[24:27]
	v_mfma_f32_16x16x32_bf16 v[28:31], v[68:71], v[56:59], v[28:31]
	v_mfma_f32_16x16x32_bf16 v[32:35], v[72:75], v[56:59], v[32:35]
	v_mfma_f32_16x16x32_bf16 v[36:39], v[76:79], v[56:59], v[36:39]
	v_mfma_f32_16x16x32_bf16 v[40:43], v[64:67], v[60:63], v[40:43]
	v_mfma_f32_16x16x32_bf16 v[44:47], v[68:71], v[60:63], v[44:47]
	v_mfma_f32_16x16x32_bf16 v[48:51], v[72:75], v[60:63], v[48:51]
	v_mfma_f32_16x16x32_bf16 v[52:55], v[76:79], v[60:63], v[52:55]
	global_load_dwordx4 v[56:59], v[8:9], off offset:0
	global_load_dwordx4 v[60:63], v[10:11], off offset:0
	global_load_dwordx4 v[64:67], v[12:13], off offset:0
	global_load_dwordx4 v[68:71], v[14:15], off offset:0
	global_load_dwordx4 v[72:75], v[16:17], off offset:0
	global_load_dwordx4 v[76:79], v[18:19], off offset:0
	s_waitcnt vmcnt(18)
	v_mfma_f32_16x16x32_bf16 v[24:27], v[88:91], v[80:83], v[24:27]
	v_mfma_f32_16x16x32_bf16 v[28:31], v[92:95], v[80:83], v[28:31]
	v_mfma_f32_16x16x32_bf16 v[32:35], v[96:99], v[80:83], v[32:35]
	v_mfma_f32_16x16x32_bf16 v[36:39], v[100:103], v[80:83], v[36:39]
	v_mfma_f32_16x16x32_bf16 v[40:43], v[88:91], v[84:87], v[40:43]
	v_mfma_f32_16x16x32_bf16 v[44:47], v[92:95], v[84:87], v[44:47]
	v_mfma_f32_16x16x32_bf16 v[48:51], v[96:99], v[84:87], v[48:51]
	v_mfma_f32_16x16x32_bf16 v[52:55], v[100:103], v[84:87], v[52:55]
	global_load_dwordx4 v[80:83], v[8:9], off offset:64
	global_load_dwordx4 v[84:87], v[10:11], off offset:64
	global_load_dwordx4 v[88:91], v[12:13], off offset:64
	global_load_dwordx4 v[92:95], v[14:15], off offset:64
	global_load_dwordx4 v[96:99], v[16:17], off offset:64
	global_load_dwordx4 v[100:103], v[18:19], off offset:64
	s_waitcnt vmcnt(18)
	v_mfma_f32_16x16x32_bf16 v[24:27], v[112:115], v[104:107], v[24:27]
	v_mfma_f32_16x16x32_bf16 v[28:31], v[116:119], v[104:107], v[28:31]
	v_mfma_f32_16x16x32_bf16 v[32:35], v[120:123], v[104:107], v[32:35]
	v_mfma_f32_16x16x32_bf16 v[36:39], v[124:127], v[104:107], v[36:39]
	v_mfma_f32_16x16x32_bf16 v[40:43], v[112:115], v[108:111], v[40:43]
	v_mfma_f32_16x16x32_bf16 v[44:47], v[116:119], v[108:111], v[44:47]
	v_mfma_f32_16x16x32_bf16 v[48:51], v[120:123], v[108:111], v[48:51]
	v_mfma_f32_16x16x32_bf16 v[52:55], v[124:127], v[108:111], v[52:55]
	global_load_dwordx4 v[104:107], v[8:9], off offset:128
	global_load_dwordx4 v[108:111], v[10:11], off offset:128
	global_load_dwordx4 v[112:115], v[12:13], off offset:128
	global_load_dwordx4 v[116:119], v[14:15], off offset:128
	global_load_dwordx4 v[120:123], v[16:17], off offset:128
	global_load_dwordx4 v[124:127], v[18:19], off offset:128
	s_waitcnt vmcnt(18)
	v_mfma_f32_16x16x32_bf16 v[24:27], v[136:139], v[128:131], v[24:27]
	v_mfma_f32_16x16x32_bf16 v[28:31], v[140:143], v[128:131], v[28:31]
	v_mfma_f32_16x16x32_bf16 v[32:35], v[144:147], v[128:131], v[32:35]
	v_mfma_f32_16x16x32_bf16 v[36:39], v[148:151], v[128:131], v[36:39]
	v_mfma_f32_16x16x32_bf16 v[40:43], v[136:139], v[132:135], v[40:43]
	v_mfma_f32_16x16x32_bf16 v[44:47], v[140:143], v[132:135], v[44:47]
	v_mfma_f32_16x16x32_bf16 v[48:51], v[144:147], v[132:135], v[48:51]
	v_mfma_f32_16x16x32_bf16 v[52:55], v[148:151], v[132:135], v[52:55]
	global_load_dwordx4 v[128:131], v[8:9], off offset:192
	global_load_dwordx4 v[132:135], v[10:11], off offset:192
	global_load_dwordx4 v[136:139], v[12:13], off offset:192
	global_load_dwordx4 v[140:143], v[14:15], off offset:192
	global_load_dwordx4 v[144:147], v[16:17], off offset:192
	global_load_dwordx4 v[148:151], v[18:19], off offset:192
	s_sub_i32 s12, s12, 4
	s_cmp_lg_u32 s12, 0
	s_cbranch_scc1 .Lcg0_grp
; #define GAS __attribute__((address_space(1)))
; DI u32x4 pack8(f32x4 a, f32x4 b) { u32x4 w; w.x = pk2(a[0], a[1]); w.y = pk2(a[2], a[3]); w.z = pk2(b[0], b[1]); w.w = pk2(b[2], b[3]); return w; }
;     DI void operator()(const AccT& acc, const pg8::Unit& u, int wr, int wc, int fr, int fq) const {
;         const int row0 = u.pm * 256 + wr * 64 + fr, col0 = u.pn * 256 + wc * 32 + 8 * fq;
; #pragma unroll
;         for (int ai = 0; ai < 2; ++ai)
; #pragma unroll
;             for (int m = 0; m < 4; ++m) { bf16_t* rowp = O + (size_t)(row0 + ai * 128 + m * 16) * ldc + col0;
; #pragma unroll
;                 for (int bj = 0; bj < 2; ++bj) *(GAS u32x4*)(rowp + bj * 128) = pack8(acc[ai][bj][m][0], acc[ai][bj][m][1]); }
;     }
	s_waitcnt vmcnt(18)
	v_mfma_f32_16x16x32_bf16 v[24:27], v[64:67], v[56:59], v[24:27]
	v_mfma_f32_16x16x32_bf16 v[28:31], v[68:71], v[56:59], v[28:31]
	v_mfma_f32_16x16x32_bf16 v[32:35], v[72:75], v[56:59], v[32:35]
	v_mfma_f32_16x16x32_bf16 v[36:39], v[76:79], v[56:59], v[36:39]
	v_mfma_f32_16x16x32_bf16 v[40:43], v[64:67], v[60:63], v[40:43]
	v_mfma_f32_16x16x32_bf16 v[44:47], v[68:71], v[60:63], v[44:47]
	v_mfma_f32_16x16x32_bf16 v[48:51], v[72:75], v[60:63], v[48:51]
	v_mfma_f32_16x16x32_bf16 v[52:55], v[76:79], v[60:63], v[52:55]
	s_waitcnt vmcnt(12)
	v_mfma_f32_16x16x32_bf16 v[24:27], v[88:91], v[80:83], v[24:27]
	v_mfma_f32_16x16x32_bf16 v[28:31], v[92:95], v[80:83], v[28:31]
	v_mfma_f32_16x16x32_bf16 v[32:35], v[96:99], v[80:83], v[32:35]
	v_mfma_f32_16x16x32_bf16 v[36:39], v[100:103], v[80:83], v[36:39]
	v_mfma_f32_16x16x32_bf16 v[40:43], v[88:91], v[84:87], v[40:43]
	v_mfma_f32_16x16x32_bf16 v[44:47], v[92:95], v[84:87], v[44:47]
	v_mfma_f32_16x16x32_bf16 v[48:51], v[96:99], v[84:87], v[48:51]
	v_mfma_f32_16x16x32_bf16 v[52:55], v[100:103], v[84:87], v[52:55]
	s_waitcnt vmcnt(6)
	v_mfma_f32_16x16x32_bf16 v[24:27], v[112:115], v[104:107], v[24:27]
	v_mfma_f32_16x16x32_bf16 v[28:31], v[116:119], v[104:107], v[28:31]
	v_mfma_f32_16x16x32_bf16 v[32:35], v[120:123], v[104:107], v[32:35]
	v_mfma_f32_16x16x32_bf16 v[36:39], v[124:127], v[104:107], v[36:39]
	v_mfma_f32_16x16x32_bf16 v[40:43], v[112:115], v[108:111], v[40:43]
	v_mfma_f32_16x16x32_bf16 v[44:47], v[116:119], v[108:111], v[44:47]
	v_mfma_f32_16x16x32_bf16 v[48:51], v[120:123], v[108:111], v[48:51]
	v_mfma_f32_16x16x32_bf16 v[52:55], v[124:127], v[108:111], v[52:55]
	s_waitcnt vmcnt(0)
	v_mfma_f32_16x16x32_bf16 v[24:27], v[136:139], v[128:131], v[24:27]
	v_mfma_f32_16x16x32_bf16 v[28:31], v[140:143], v[128:131], v[28:31]
	v_mfma_f32_16x16x32_bf16 v[32:35], v[144:147], v[128:131], v[32:35]
	v_mfma_f32_16x16x32_bf16 v[36:39], v[148:151], v[128:131], v[36:39]
	v_mfma_f32_16x16x32_bf16 v[40:43], v[136:139], v[132:135], v[40:43]
	v_mfma_f32_16x16x32_bf16 v[44:47], v[140:143], v[132:135], v[44:47]
	v_mfma_f32_16x16x32_bf16 v[48:51], v[144:147], v[132:135], v[48:51]
	v_mfma_f32_16x16x32_bf16 v[52:55], v[148:151], v[132:135], v[52:55]
	s_nop 7
	v_cvt_pk_bf16_f32 v154, v24, v25
	v_cvt_pk_bf16_f32 v155, v26, v27
	global_store_dwordx2 v4, v[154:155], s[10:11] offset:0
	s_nop 1
	v_cvt_pk_bf16_f32 v154, v28, v29
	v_cvt_pk_bf16_f32 v155, v30, v31
	global_store_dwordx2 v4, v[154:155], s[10:11] offset:32
	s_nop 1
	v_cvt_pk_bf16_f32 v154, v32, v33
	v_cvt_pk_bf16_f32 v155, v34, v35
	global_store_dwordx2 v4, v[154:155], s[10:11] offset:64
	s_nop 1
	v_cvt_pk_bf16_f32 v154, v36, v37
	v_cvt_pk_bf16_f32 v155, v38, v39
	global_store_dwordx2 v4, v[154:155], s[10:11] offset:96
	s_nop 1
	v_cvt_pk_bf16_f32 v154, v40, v41
	v_cvt_pk_bf16_f32 v155, v42, v43
	v_add_u32_e32 v156, 0x8000, v4
	global_store_dwordx2 v156, v[154:155], s[10:11]
	s_nop 1
	v_cvt_pk_bf16_f32 v154, v44, v45
	v_cvt_pk_bf16_f32 v155, v46, v47
	v_add_u32_e32 v156, 0x8020, v4
	global_store_dwordx2 v156, v[154:155], s[10:11]
	s_nop 1
	v_cvt_pk_bf16_f32 v154, v48, v49
	v_cvt_pk_bf16_f32 v155, v50, v51
	v_add_u32_e32 v156, 0x8040, v4
	global_store_dwordx2 v156, v[154:155], s[10:11]
	s_nop 1
	v_cvt_pk_bf16_f32 v154, v52, v53
	v_cvt_pk_bf16_f32 v155, v54, v55
	v_add_u32_e32 v156, 0x8060, v4
	global_store_dwordx2 v156, v[154:155], s[10:11]
	s_nop 1
	v_readlane_b32 s0, v252, 55
	s_mul_i32 s0, s0, 2
	s_add_i32 s2, s2, s0
	s_branch .Lcg0_tile
